# MLA attention fast loop: fused latch/header, DMA issue staggered between wave halves (header copy for waves 0-3, tail copy for waves 4-7)
# baseline (speedup 1.0000x reference)
; DI int ltid() { int t = threadIdx.x; asm volatile("" : "+v"(t)); return t; }
; template <int DK, int DV, int NM, bool CAUSAL> ...
;     ...
;   const int tid = ltid(), lane = tid & 63, wave = tid >> 6, h = lane >> 5, l31 = lane & 31;
;   const int wq = (NM == 2) ? (wave & 3) : wave;
;   const int mymap = (NM == 2) ? (wave >> 2) : 0;
;   const int q0w = q0 + wq * 32;
;   bf16x8 qf[NKC16];
;   f32x16 o[NDVB];
; #pragma unroll
;   for (int d = 0; d < NDVB; ++d)
; #pragma unroll
;     for (int i = 0; i < 16; ++i) o[d][i] = 0.f;
;   f32x16 lacc;
; #pragma unroll
;   for (int i = 0; i < 16; ++i) lacc[i] = 0.f;
;   u4 onesu; onesu.x = onesu.y = onesu.z = onesu.w = 0x3F803F80u;
;   const bf16x8 ones = __builtin_bit_cast(bf16x8, onesu);
;   const int wu = __builtin_amdgcn_readfirstlane(wave);
;   const int krow = lane >> 4, kslot = lane & 15;
;   const int vrow = lane >> 3, vslot = lane & 7;
;   auto issue = [&](int kt) {
;     char* st = smem + (kt & 3) * STAGE;
; #pragma unroll
;     for (int i = 0; i < 2; ++i) {
;       const int r = (wu * 2 + i) * 4 + krow;
;       const int c = kslot ^ (r & 15);
;       if (KCHV == 16 || c < KCHV)
;         __builtin_amdgcn_global_load_lds((const unsigned*)(Kg + (size_t)(kt * 64 + r) * ldk + c * 8), (unsigned*)(st + (wu * 2 + i) * 1024), 16, 0, 0);
;     }
; #pragma unroll
;     for (int i = 0; i < NVI; ++i) {
;       const int d = (wu * NVI + i) * 8 + vrow;
;       const int c = vslot ^ ((d >> 1) & 7);
;       __builtin_amdgcn_global_load_lds((const unsigned*)(Vt + (size_t)d * ldv + kt * 64 + c * 8), (unsigned*)(st + KBYTES + (wu * NVI + i) * 1024), 16, 0, 0);
;     }
;   };
;   asm volatile("s_waitcnt vmcnt(0)" ::: "memory");
;   __syncthreads();
;   if (0 < nkt) issue(0);
;   if (1 < nkt) issue(1);
;   if (2 < nkt) issue(2);
;   {
;     const bf16_t* qp = Q + (size_t)(wq * 32 + l31) * ldq + mymap * DK + h * 8;
; #pragma unroll
;     for (int kc = 0; kc < NKC16; ++kc) qf[kc] = *(const bf16x8*)(qp + kc * 16);
; #pragma unroll
;     for (int kc = 0; kc < NKC16; ++kc) asm volatile("" : "+v"(qf[kc]));
;   }
.LBB0_50:
	s_or_b64 exec, exec, s[18:19]
	s_xor_b64 s[18:19], s[8:9], -1
	s_and_b64 s[8:9], s[8:9], exec
	s_cselect_b32 s65, s35, s34
	s_or_b32 s8, s65, s61
	s_mul_hi_u32 s9, s8, 0x600
	s_mulk_i32 s8, 0x600
	s_add_u32 s8, s62, s8
	s_addc_u32 s9, s63, s9
	v_lshlrev_b32_e32 v22, 5, v9
	v_and_b32_e32 v23, 31, v6
	v_lshrrev_b32_e32 v19, 5, v10
	v_or_b32_e32 v0, v22, v23
	v_mov_b64_e32 v[2:3], s[8:9]
	v_mad_i64_i32 v[120:121], s[8:9], v0, s33, v[2:3]
	v_lshlrev_b32_e32 v0, 4, v19
	v_lshl_add_u64 v[2:3], v[120:121], 0, v[0:1]
	flat_load_dwordx4 v[116:119], v[2:3]
	flat_load_dwordx4 v[112:115], v[2:3] offset:32
	flat_load_dwordx4 v[108:111], v[2:3] offset:64
	flat_load_dwordx4 v[104:107], v[2:3] offset:96
	flat_load_dwordx4 v[100:103], v[2:3] offset:128
	flat_load_dwordx4 v[96:99], v[2:3] offset:160
	v_lshl_add_u64 v[2:3], v[122:123], 0, s[94:95]
	s_add_i32 m0, s64, 0x10000
	v_mov_b32_e32 v17, v1
	global_load_lds_dwordx4 v[2:3], off
	v_bfe_u32 v21, v6, 1, 3
	v_add_u32_e32 v20, s31, v8
	v_lshl_add_u64 v[126:127], s[0:1], 0, v[16:17]
	v_bitop3_b32 v16, v19, v21, 2 bitop3:0x36
	v_bitop3_b32 v17, v19, v21, 4 bitop3:0x36
	v_bitop3_b32 v25, v19, v21, 6 bitop3:0x36
	v_ashrrev_i32_e32 v21, 31, v20
	v_lshrrev_b32_e32 v0, 1, v6
	v_and_b32_e32 v24, 7, v7
	v_lshlrev_b32_e32 v134, 4, v16
	v_lshlrev_b32_e32 v132, 4, v17
	v_lshlrev_b64 v[16:17], 12, v[20:21]
	v_mov_b32_e32 v14, v1
	v_mov_b32_e32 v15, v1
	v_bitop3_b32 v0, v0, v19, 7 bitop3:0x6c
	v_xor_b32_e32 v26, v19, v18
	v_bitop3_b32 v27, v19, v18, 2 bitop3:0x36
	v_bitop3_b32 v28, v19, v18, 4 bitop3:0x36
	v_bitop3_b32 v29, v19, v18, 6 bitop3:0x36
	v_bitop3_b32 v30, v19, v18, 8 bitop3:0x36
	v_bitop3_b32 v18, v19, v18, 10 bitop3:0x36
	v_add_u32_e32 v140, s65, v22
	v_lshl_or_b32 v16, v24, 4, v16
	s_add_i32 s8, s65, 0x100
	v_lshl_add_u64 v[124:125], v[4:5], 1, s[0:1]
	v_mov_b32_e32 v2, v1
	v_mov_b32_e32 v3, v1
	v_mov_b32_e32 v4, v1
	v_mov_b32_e32 v5, v1
	v_mov_b32_e32 v6, v1
	v_mov_b32_e32 v7, v1
	v_mov_b32_e32 v8, v1
	v_mov_b32_e32 v9, v1
	v_mov_b32_e32 v10, v1
	v_mov_b32_e32 v11, v1
	v_mov_b32_e32 v12, v1
	v_mov_b32_e32 v13, v1
	v_lshlrev_b32_e32 v144, 8, v23
	v_lshlrev_b32_e32 v139, 7, v23
	v_lshlrev_b32_e32 v130, 2, v19
	v_lshlrev_b32_e32 v135, 4, v0
	v_lshlrev_b32_e32 v131, 4, v25
	v_lshlrev_b32_e32 v147, 4, v26
	v_lshlrev_b32_e32 v146, 4, v27
	v_lshlrev_b32_e32 v145, 4, v28
	v_lshlrev_b32_e32 v143, 4, v29
	v_lshlrev_b32_e32 v142, 4, v30
	v_lshlrev_b32_e32 v141, 4, v18
	v_or_b32_e32 v133, v140, v23
	v_lshl_add_u64 v[128:129], s[16:17], 0, v[16:17]
	s_lshr_b32 s67, s8, 6
	v_mov_b32_e32 v0, v1
	v_mov_b64_e32 v[30:31], v[14:15]
	v_mov_b64_e32 v[46:47], v[14:15]
	v_mov_b64_e32 v[62:63], v[14:15]
	s_mov_b32 s68, 0
	v_or_b32_e32 v148, 31, v140
	s_lshl_b32 s65, s30, 11
	s_add_i32 s66, s67, -2
	v_mov_b64_e32 v[28:29], v[12:13]
	v_mov_b64_e32 v[26:27], v[10:11]
	v_mov_b64_e32 v[24:25], v[8:9]
	v_mov_b64_e32 v[22:23], v[6:7]
	v_mov_b64_e32 v[20:21], v[4:5]
	v_mov_b64_e32 v[18:19], v[2:3]
	v_mov_b64_e32 v[16:17], v[0:1]
	v_mov_b64_e32 v[44:45], v[12:13]
	v_mov_b64_e32 v[42:43], v[10:11]
	v_mov_b64_e32 v[40:41], v[8:9]
	v_mov_b64_e32 v[38:39], v[6:7]
	v_mov_b64_e32 v[36:37], v[4:5]
	v_mov_b64_e32 v[34:35], v[2:3]
	v_mov_b64_e32 v[32:33], v[0:1]
	s_mov_b32 s69, 0
	v_mov_b64_e32 v[60:61], v[12:13]
	v_mov_b64_e32 v[58:59], v[10:11]
	v_mov_b64_e32 v[56:57], v[8:9]
	v_mov_b64_e32 v[54:55], v[6:7]
	v_mov_b64_e32 v[52:53], v[4:5]
	v_mov_b64_e32 v[50:51], v[2:3]
	v_mov_b64_e32 v[48:49], v[0:1]
	v_mov_b32_e32 v248, v1
	v_mov_b32_e32 v249, v1
	v_readfirstlane_b32 s101, v140
	v_readfirstlane_b32 s100, v195
	s_nop 3
	s_lshr_b32 s100, s100, 8
	s_waitcnt vmcnt(0) lgkmcnt(0)
	s_branch .LBB0_52

; template <int DK, int DV, int NM, bool CAUSAL> ...
;     ...
;   auto issue = [&](int kt) {
;     char* st = smem + (kt & 3) * STAGE;
; #pragma unroll
;     for (int i = 0; i < 2; ++i) {
;       const int r = (wu * 2 + i) * 4 + krow;
;       const int c = kslot ^ (r & 15);
;       if (KCHV == 16 || c < KCHV)
;         __builtin_amdgcn_global_load_lds((const unsigned*)(Kg + (size_t)(kt * 64 + r) * ldk + c * 8), (unsigned*)(st + (wu * 2 + i) * 1024), 16, 0, 0);
;     }
; #pragma unroll
;     for (int i = 0; i < NVI; ++i) {
;       const int d = (wu * NVI + i) * 8 + vrow;
;       const int c = vslot ^ ((d >> 1) & 7);
;       __builtin_amdgcn_global_load_lds((const unsigned*)(Vt + (size_t)d * ldv + kt * 64 + c * 8), (unsigned*)(st + KBYTES + (wu * NVI + i) * 1024), 16, 0, 0);
;     }
;   };
.Lmy_m53:
	s_and_b32 s30, s8, 3
	s_mulk_i32 s30, 0x6000
	v_add_u32_e32 v0, s68, v136
	s_and_saveexec_b64 s[8:9], s[4:5]
	s_cbranch_execz .LBB0_55
	v_add_u32_e32 v2, 0xc0, v0
	v_mad_i64_i32 v[2:3], s[70:71], v2, s33, v[126:127]
	s_add_i32 m0, s30, s65
	s_nop 0
	global_load_lds_dwordx4 v[2:3], off

; template <int DK, int DV, int NM, bool CAUSAL> ...
;     ...
;   for (int kt = 0; kt < nkt; ++kt) {
;     if (kt + 2 < nkt) asm volatile("s_waitcnt vmcnt(%0)" ::"n"(2 * NLD) : "memory");
;     else if (kt + 1 < nkt) asm volatile("s_waitcnt vmcnt(%0)" ::"n"(NLD) : "memory");
;     else asm volatile("s_waitcnt vmcnt(0)" ::: "memory");
;     asm volatile("s_waitcnt lgkmcnt(0)" ::: "memory");
;     __builtin_amdgcn_s_barrier();
;     if (kt + 3 < nkt) issue(kt + 3);
;     const bool skip = CAUSAL && (kt * 64 > q0w + 31);
;     if (!skip) {
;       const char* base = smem + (kt & 3) * STAGE;
;       f32x16 s[2];
; #pragma unroll
;       for (int sb = 0; sb < 2; ++sb) {
; #pragma unroll
;         for (int i = 0; i < 16; ++i) s[sb][i] = 0.f;
;         const char* pk = base + (sb * 32 + l31) * 256;
; #pragma unroll
;         for (int kc = 0; kc < NKC16; ++kc) {
;           const bf16x8 a = *(const bf16x8*)(pk + (((mymap * (DK / 8) + kc * 2 + h) ^ (l31 & 15)) * 16));
;           s[sb] = MFMA(a, qf[kc], s[sb]);
;         }
;         __builtin_amdgcn_sched_barrier(0);
;       }
;       const bool need_mask = CAUSAL && (kt * 64 + 63 > q0w);
;       const char* pv = base + KBYTES + l31 * 128;
;       const int vsw = (l31 >> 1) & 7;
;       bf16x8 pf[4];
;       auto expo = [&](int sb) {
; #pragma unroll
;         for (int i = 0; i < 16; ++i) {
;           float pz = __builtin_amdgcn_exp2f(s[sb][i]);
;           if (need_mask) {
;             const int key = kt * 64 + sb * 32 + crow(i, h);
;             if (key > q0w + l31) pz = 0.f;
;           }
;           s[sb][i] = pz;
;         }
; #pragma unroll
;         for (int k2 = 0; k2 < 2; ++k2) {
;           u4 pu;
;           pu.x = pack2(s[sb][k2 * 8 + 0], s[sb][k2 * 8 + 1]);
;           pu.y = pack2(s[sb][k2 * 8 + 2], s[sb][k2 * 8 + 3]);
;           pu.z = pack2(s[sb][k2 * 8 + 4], s[sb][k2 * 8 + 5]);
;           pu.w = pack2(s[sb][k2 * 8 + 6], s[sb][k2 * 8 + 7]);
;           pf[sb * 2 + k2] = __builtin_bit_cast(bf16x8, pu);
;         }
;       };
;       auto pvmm = [&](int ks) {
;         lacc = MFMA(ones, pf[ks], lacc);
; #pragma unroll
;         for (int d = 0; d < NDVB; ++d) {
;           const u4 au = *(const u4*)(pv + d * 32 * 128 + (((ks * 2 + h) ^ vsw) * 16));
;           o[d] = MFMA(__builtin_bit_cast(bf16x8, au), pf[ks], o[d]);
;         }
;       };
;       expo(0);
;       pvmm(0); pvmm(1);
;       expo(1);
.Lmy_mfast_top:
	s_and_b32 s8, s69, 3
	s_mulk_i32 s8, 0x6000
	v_or_b32_e32 v0, s8, v144
	v_add_u32_e32 v6, v0, v147
	v_add_u32_e32 v7, v0, v146
	v_add_u32_e32 v8, v0, v145
	v_add_u32_e32 v9, v0, v143
	v_add_u32_e32 v10, v0, v142
	v_add_u32_e32 v11, v0, v141
	ds_read_b128 v[212:215], v6
	ds_read_b128 v[216:219], v7
	ds_read_b128 v[220:223], v8
	ds_read_b128 v[224:227], v9
	ds_read_b128 v[228:231], v10
	ds_read_b128 v[232:235], v11
	v_or_b32_e32 v0, s8, v139
	v_add_u32_e32 v12, v0, v135
	v_add_u32_e32 v13, v0, v134
	v_add_u32_e32 v14, v0, v132
	v_add_u32_e32 v15, v0, v131
	ds_read_b128 v[236:239], v12 offset:16384
	ds_read_b128 v[240:243], v12 offset:20480
	s_waitcnt lgkmcnt(7)
	v_mfma_f32_32x32x16_bf16 v[80:95], v[212:215], v[116:119], 0
	ds_read_b128 v[212:215], v6 offset:8192
	s_waitcnt lgkmcnt(7)
	v_mfma_f32_32x32x16_bf16 v[80:95], v[216:219], v[112:115], v[80:95]
	ds_read_b128 v[216:219], v7 offset:8192
	s_waitcnt lgkmcnt(7)
	v_mfma_f32_32x32x16_bf16 v[80:95], v[220:223], v[108:111], v[80:95]
	ds_read_b128 v[220:223], v8 offset:8192
	s_waitcnt lgkmcnt(7)
	v_mfma_f32_32x32x16_bf16 v[80:95], v[224:227], v[104:107], v[80:95]
	ds_read_b128 v[224:227], v9 offset:8192
	s_waitcnt lgkmcnt(7)
	v_mfma_f32_32x32x16_bf16 v[80:95], v[228:231], v[100:103], v[80:95]
	ds_read_b128 v[228:231], v10 offset:8192
	s_waitcnt lgkmcnt(7)
	v_mfma_f32_32x32x16_bf16 v[80:95], v[232:235], v[96:99], v[80:95]
	ds_read_b128 v[232:235], v11 offset:8192
	s_waitcnt lgkmcnt(5)
	v_mfma_f32_32x32x16_bf16 v[64:79], v[212:215], v[116:119], 0
	ds_read_b128 v[212:215], v13 offset:16384
	s_waitcnt lgkmcnt(5)
	v_mfma_f32_32x32x16_bf16 v[64:79], v[216:219], v[112:115], v[64:79]
	ds_read_b128 v[216:219], v13 offset:20480
	s_waitcnt lgkmcnt(5)
	v_mfma_f32_32x32x16_bf16 v[64:79], v[220:223], v[108:111], v[64:79]
	ds_read_b128 v[220:223], v14 offset:16384
	s_waitcnt lgkmcnt(5)
	v_mfma_f32_32x32x16_bf16 v[64:79], v[224:227], v[104:107], v[64:79]
	ds_read_b128 v[224:227], v14 offset:20480
	s_waitcnt lgkmcnt(5)
	v_mfma_f32_32x32x16_bf16 v[64:79], v[228:231], v[100:103], v[64:79]
	ds_read_b128 v[228:231], v15 offset:16384
	s_waitcnt lgkmcnt(5)
	v_mfma_f32_32x32x16_bf16 v[64:79], v[232:235], v[96:99], v[64:79]
	ds_read_b128 v[232:235], v15 offset:20480
	v_exp_f32_e32 v80, v80
	v_exp_f32_e32 v81, v81
	v_exp_f32_e32 v82, v82
	v_exp_f32_e32 v83, v83
	v_exp_f32_e32 v84, v84
	v_exp_f32_e32 v85, v85
	v_exp_f32_e32 v86, v86
	v_exp_f32_e32 v87, v87
	v_add_f32_e32 v248, v248, v80
	v_add_f32_e32 v249, v249, v81
	v_add_f32_e32 v248, v248, v82
	v_add_f32_e32 v249, v249, v83
	v_add_f32_e32 v248, v248, v84
	v_add_f32_e32 v249, v249, v85
	v_add_f32_e32 v248, v248, v86
	v_add_f32_e32 v249, v249, v87
	v_cvt_pk_bf16_f32 v186, v80, v81
	v_cvt_pk_bf16_f32 v187, v82, v83
	v_cvt_pk_bf16_f32 v188, v84, v85
	v_cvt_pk_bf16_f32 v189, v86, v87
	s_nop 0
	v_mfma_f32_32x32x16_bf16 v[32:47], v[236:239], v[186:189], v[32:47]
	v_exp_f32_e32 v88, v88
	v_exp_f32_e32 v89, v89
	v_exp_f32_e32 v90, v90
	v_exp_f32_e32 v91, v91
	v_exp_f32_e32 v92, v92
	v_exp_f32_e32 v93, v93
	v_mfma_f32_32x32x16_bf16 v[16:31], v[240:243], v[186:189], v[16:31]
	v_exp_f32_e32 v94, v94
	v_exp_f32_e32 v95, v95
	v_add_f32_e32 v248, v248, v88
	v_add_f32_e32 v249, v249, v89
	v_add_f32_e32 v248, v248, v90
	v_add_f32_e32 v249, v249, v91
	v_add_f32_e32 v248, v248, v92
	v_add_f32_e32 v249, v249, v93
	v_add_f32_e32 v248, v248, v94
	v_add_f32_e32 v249, v249, v95
	v_cvt_pk_bf16_f32 v190, v88, v89
	v_cvt_pk_bf16_f32 v191, v90, v91
	v_cvt_pk_bf16_f32 v192, v92, v93
	v_cvt_pk_bf16_f32 v193, v94, v95
	s_nop 0
	s_waitcnt lgkmcnt(5)
	v_mfma_f32_32x32x16_bf16 v[32:47], v[212:215], v[190:193], v[32:47]
	v_exp_f32_e32 v64, v64
	v_exp_f32_e32 v65, v65
	v_exp_f32_e32 v66, v66
	v_exp_f32_e32 v67, v67
	v_exp_f32_e32 v68, v68
	v_exp_f32_e32 v69, v69
	s_waitcnt lgkmcnt(4)
	v_mfma_f32_32x32x16_bf16 v[16:31], v[216:219], v[190:193], v[16:31]
	v_exp_f32_e32 v70, v70
	v_exp_f32_e32 v71, v71
	v_add_f32_e32 v248, v248, v64
	v_add_f32_e32 v249, v249, v65
	v_add_f32_e32 v248, v248, v66
	v_add_f32_e32 v249, v249, v67
	v_add_f32_e32 v248, v248, v68
	v_add_f32_e32 v249, v249, v69
	v_add_f32_e32 v248, v248, v70
	v_add_f32_e32 v249, v249, v71
	v_cvt_pk_bf16_f32 v244, v64, v65
	v_cvt_pk_bf16_f32 v245, v66, v67
	v_cvt_pk_bf16_f32 v246, v68, v69
	v_cvt_pk_bf16_f32 v247, v70, v71
	s_nop 0
	s_waitcnt lgkmcnt(3)
	v_mfma_f32_32x32x16_bf16 v[32:47], v[220:223], v[244:247], v[32:47]
	v_exp_f32_e32 v72, v72
	v_exp_f32_e32 v73, v73
	v_exp_f32_e32 v74, v74
	v_exp_f32_e32 v75, v75
	v_exp_f32_e32 v76, v76
	v_exp_f32_e32 v77, v77
	s_waitcnt lgkmcnt(2)
	v_mfma_f32_32x32x16_bf16 v[16:31], v[224:227], v[244:247], v[16:31]
	v_exp_f32_e32 v78, v78
	v_exp_f32_e32 v79, v79
	v_add_f32_e32 v248, v248, v72
	v_add_f32_e32 v249, v249, v73
	v_add_f32_e32 v248, v248, v74
	v_add_f32_e32 v249, v249, v75
	v_add_f32_e32 v248, v248, v76
	v_add_f32_e32 v249, v249, v77
	v_add_f32_e32 v248, v248, v78
	v_add_f32_e32 v249, v249, v79
	v_cvt_pk_bf16_f32 v2, v72, v73
	v_cvt_pk_bf16_f32 v3, v74, v75
	v_cvt_pk_bf16_f32 v4, v76, v77
	v_cvt_pk_bf16_f32 v5, v78, v79
	s_nop 0
	s_waitcnt lgkmcnt(1)
	v_mfma_f32_32x32x16_bf16 v[32:47], v[228:231], v[2:5], v[32:47]
	s_waitcnt lgkmcnt(0)
	v_mfma_f32_32x32x16_bf16 v[16:31], v[232:235], v[2:5], v[16:31]
.Lmy_mft:
	s_add_i32 s69, s69, 1
	s_add_i32 s68, s68, 64
	v_lshl_add_u64 v[128:129], v[128:129], 0, s[92:93]
	s_cmp_lg_u32 s66, s69
	s_cbranch_scc0 .LBB0_60
	s_waitcnt vmcnt(6)
	s_add_i32 s8, s69, 3
	s_cmp_ge_u32 s8, s67
	s_barrier
	s_cbranch_scc1 .LBB0_58
	s_add_i32 s30, s68, 63
	s_cmp_le_i32 s30, s101
	s_cbranch_scc0 .Lmy_m53
	s_cmp_eq_u32 s100, 1
	s_cbranch_scc1 .Lmy_mlate
	s_and_b32 s30, s8, 3
	s_mulk_i32 s30, 0x6000
	v_add_u32_e32 v0, s68, v136
	s_and_saveexec_b64 s[8:9], s[4:5]
	s_cbranch_execz .Lmy_m55a
	v_add_u32_e32 v2, 0xc0, v0
	v_mad_i64_i32 v[2:3], s[70:71], v2, s33, v[126:127]
	s_add_i32 m0, s30, s65
	s_nop 0
	global_load_lds_dwordx4 v[2:3], off

; template <int DK, int DV, int NM, bool CAUSAL> ...
;     ...
;       const int r = (wu * 2 + i) * 4 + krow;
;       const int c = kslot ^ (r & 15);
;       if (KCHV == 16 || c < KCHV)
;         __builtin_amdgcn_global_load_lds((const unsigned*)(Kg + (size_t)(kt * 64 + r) * ldk + c * 8), (unsigned*)(st + (wu * 2 + i) * 1024), 16, 0, 0);
;     }
; #pragma unroll
;     for (int i = 0; i < NVI; ++i) {
;       const int d = (wu * NVI + i) * 8 + vrow;
;     ...
;       const char* base = smem + (kt & 3) * STAGE;
;       f32x16 s[2];
; #pragma unroll
;       for (int sb = 0; sb < 2; ++sb) {
; #pragma unroll
;         for (int i = 0; i < 16; ++i) s[sb][i] = 0.f;
;         const char* pk = base + (sb * 32 + l31) * 256;
; #pragma unroll
;         for (int kc = 0; kc < NKC16; ++kc) {
;           const bf16x8 a = *(const bf16x8*)(pk + (((mymap * (DK / 8) + kc * 2 + h) ^ (l31 & 15)) * 16));
;           s[sb] = MFMA(a, qf[kc], s[sb]);
;         }
;         __builtin_amdgcn_sched_barrier(0);
;       }
;       const bool need_mask = CAUSAL && (kt * 64 + 63 > q0w);
;       const char* pv = base + KBYTES + l31 * 128;
;       const int vsw = (l31 >> 1) & 7;
;       bf16x8 pf[4];
;       auto expo = [&](int sb) {
; #pragma unroll
;         for (int i = 0; i < 16; ++i) {
;           float pz = __builtin_amdgcn_exp2f(s[sb][i]);
;           if (need_mask) {
;             const int key = kt * 64 + sb * 32 + crow(i, h);
;             if (key > q0w + l31) pz = 0.f;
;           }
;           s[sb][i] = pz;
;         }
; #pragma unroll
;         for (int k2 = 0; k2 < 2; ++k2) {
;           u4 pu;
;           pu.x = pack2(s[sb][k2 * 8 + 0], s[sb][k2 * 8 + 1]);
;           pu.y = pack2(s[sb][k2 * 8 + 2], s[sb][k2 * 8 + 3]);
;           pu.z = pack2(s[sb][k2 * 8 + 4], s[sb][k2 * 8 + 5]);
;           pu.w = pack2(s[sb][k2 * 8 + 6], s[sb][k2 * 8 + 7]);
;           pf[sb * 2 + k2] = __builtin_bit_cast(bf16x8, pu);
;         }
;       };
;       auto pvmm = [&](int ks) {
;         lacc = MFMA(ones, pf[ks], lacc);
; #pragma unroll
;         for (int d = 0; d < NDVB; ++d) {
;           const u4 au = *(const u4*)(pv + d * 32 * 128 + (((ks * 2 + h) ^ vsw) * 16));
;           o[d] = MFMA(__builtin_bit_cast(bf16x8, au), pf[ks], o[d]);
;         }
;       };
;       expo(0);
;       pvmm(0); pvmm(1);
;       expo(1);
;       pvmm(2); pvmm(3);
;       __builtin_amdgcn_sched_barrier(0);
.Lmy_m57a:
	s_or_b64 exec, exec, s[8:9]
	s_add_i32 s8, s30, s64
	s_add_i32 m0, s8, 0x4000
	s_nop 0
	global_load_lds_dwordx4 v[128:129], off
	s_branch .Lmy_mfast_top
.Lmy_mlate:
	s_and_b32 s8, s69, 3
	s_mulk_i32 s8, 0x6000
	v_or_b32_e32 v0, s8, v144
	v_add_u32_e32 v6, v0, v147
	v_add_u32_e32 v7, v0, v146
	v_add_u32_e32 v8, v0, v145
	v_add_u32_e32 v9, v0, v143
	v_add_u32_e32 v10, v0, v142
	v_add_u32_e32 v11, v0, v141
	ds_read_b128 v[212:215], v6
	ds_read_b128 v[216:219], v7
	ds_read_b128 v[220:223], v8
	ds_read_b128 v[224:227], v9
	ds_read_b128 v[228:231], v10
	ds_read_b128 v[232:235], v11
	v_or_b32_e32 v0, s8, v139
	v_add_u32_e32 v12, v0, v135
	v_add_u32_e32 v13, v0, v134
	v_add_u32_e32 v14, v0, v132
	v_add_u32_e32 v15, v0, v131
	ds_read_b128 v[236:239], v12 offset:16384
	ds_read_b128 v[240:243], v12 offset:20480
	s_waitcnt lgkmcnt(7)
	v_mfma_f32_32x32x16_bf16 v[80:95], v[212:215], v[116:119], 0
	ds_read_b128 v[212:215], v6 offset:8192
	s_waitcnt lgkmcnt(7)
	v_mfma_f32_32x32x16_bf16 v[80:95], v[216:219], v[112:115], v[80:95]
	ds_read_b128 v[216:219], v7 offset:8192
	s_waitcnt lgkmcnt(7)
	v_mfma_f32_32x32x16_bf16 v[80:95], v[220:223], v[108:111], v[80:95]
	ds_read_b128 v[220:223], v8 offset:8192
	s_waitcnt lgkmcnt(7)
	v_mfma_f32_32x32x16_bf16 v[80:95], v[224:227], v[104:107], v[80:95]
	ds_read_b128 v[224:227], v9 offset:8192
	s_waitcnt lgkmcnt(7)
	v_mfma_f32_32x32x16_bf16 v[80:95], v[228:231], v[100:103], v[80:95]
	ds_read_b128 v[228:231], v10 offset:8192
	s_waitcnt lgkmcnt(7)
	v_mfma_f32_32x32x16_bf16 v[80:95], v[232:235], v[96:99], v[80:95]
	ds_read_b128 v[232:235], v11 offset:8192
	s_waitcnt lgkmcnt(5)
	v_mfma_f32_32x32x16_bf16 v[64:79], v[212:215], v[116:119], 0
	ds_read_b128 v[212:215], v13 offset:16384
	s_waitcnt lgkmcnt(5)
	v_mfma_f32_32x32x16_bf16 v[64:79], v[216:219], v[112:115], v[64:79]
	ds_read_b128 v[216:219], v13 offset:20480
	s_waitcnt lgkmcnt(5)
	v_mfma_f32_32x32x16_bf16 v[64:79], v[220:223], v[108:111], v[64:79]
	ds_read_b128 v[220:223], v14 offset:16384
	s_waitcnt lgkmcnt(5)
	v_mfma_f32_32x32x16_bf16 v[64:79], v[224:227], v[104:107], v[64:79]
	ds_read_b128 v[224:227], v14 offset:20480
	s_waitcnt lgkmcnt(5)
	v_mfma_f32_32x32x16_bf16 v[64:79], v[228:231], v[100:103], v[64:79]
	ds_read_b128 v[228:231], v15 offset:16384
	s_waitcnt lgkmcnt(5)
	v_mfma_f32_32x32x16_bf16 v[64:79], v[232:235], v[96:99], v[64:79]
	ds_read_b128 v[232:235], v15 offset:20480
	v_exp_f32_e32 v80, v80
	v_exp_f32_e32 v81, v81
	v_exp_f32_e32 v82, v82
	v_exp_f32_e32 v83, v83
	v_exp_f32_e32 v84, v84
	v_exp_f32_e32 v85, v85
	v_exp_f32_e32 v86, v86
	v_exp_f32_e32 v87, v87
	v_add_f32_e32 v248, v248, v80
	v_add_f32_e32 v249, v249, v81
	v_add_f32_e32 v248, v248, v82
	v_add_f32_e32 v249, v249, v83
	v_add_f32_e32 v248, v248, v84
	v_add_f32_e32 v249, v249, v85
	v_add_f32_e32 v248, v248, v86
	v_add_f32_e32 v249, v249, v87
	v_cvt_pk_bf16_f32 v186, v80, v81
	v_cvt_pk_bf16_f32 v187, v82, v83
	v_cvt_pk_bf16_f32 v188, v84, v85
	v_cvt_pk_bf16_f32 v189, v86, v87
	s_nop 0
	v_mfma_f32_32x32x16_bf16 v[32:47], v[236:239], v[186:189], v[32:47]
	v_exp_f32_e32 v88, v88
	v_exp_f32_e32 v89, v89
	v_exp_f32_e32 v90, v90
	v_exp_f32_e32 v91, v91
	v_exp_f32_e32 v92, v92
	v_exp_f32_e32 v93, v93
	v_mfma_f32_32x32x16_bf16 v[16:31], v[240:243], v[186:189], v[16:31]
	v_exp_f32_e32 v94, v94
	v_exp_f32_e32 v95, v95
	v_add_f32_e32 v248, v248, v88
	v_add_f32_e32 v249, v249, v89
	v_add_f32_e32 v248, v248, v90
	v_add_f32_e32 v249, v249, v91
	v_add_f32_e32 v248, v248, v92
	v_add_f32_e32 v249, v249, v93
	v_add_f32_e32 v248, v248, v94
	v_add_f32_e32 v249, v249, v95
	v_cvt_pk_bf16_f32 v190, v88, v89
	v_cvt_pk_bf16_f32 v191, v90, v91
	v_cvt_pk_bf16_f32 v192, v92, v93
	v_cvt_pk_bf16_f32 v193, v94, v95
	s_nop 0
	s_waitcnt lgkmcnt(5)
	v_mfma_f32_32x32x16_bf16 v[32:47], v[212:215], v[190:193], v[32:47]
	v_exp_f32_e32 v64, v64
	v_exp_f32_e32 v65, v65
	v_exp_f32_e32 v66, v66
	v_exp_f32_e32 v67, v67
	v_exp_f32_e32 v68, v68
	v_exp_f32_e32 v69, v69
	s_waitcnt lgkmcnt(4)
	v_mfma_f32_32x32x16_bf16 v[16:31], v[216:219], v[190:193], v[16:31]
	v_exp_f32_e32 v70, v70
	v_exp_f32_e32 v71, v71
	v_add_f32_e32 v248, v248, v64
	v_add_f32_e32 v249, v249, v65
	v_add_f32_e32 v248, v248, v66
	v_add_f32_e32 v249, v249, v67
	v_add_f32_e32 v248, v248, v68
	v_add_f32_e32 v249, v249, v69
	v_add_f32_e32 v248, v248, v70
	v_add_f32_e32 v249, v249, v71
	v_cvt_pk_bf16_f32 v244, v64, v65
	v_cvt_pk_bf16_f32 v245, v66, v67
	v_cvt_pk_bf16_f32 v246, v68, v69
	v_cvt_pk_bf16_f32 v247, v70, v71
	s_nop 0
	s_waitcnt lgkmcnt(3)
	v_mfma_f32_32x32x16_bf16 v[32:47], v[220:223], v[244:247], v[32:47]
	v_exp_f32_e32 v72, v72
	v_exp_f32_e32 v73, v73
	v_exp_f32_e32 v74, v74
	v_exp_f32_e32 v75, v75
	v_exp_f32_e32 v76, v76
	v_exp_f32_e32 v77, v77
	s_waitcnt lgkmcnt(2)
	v_mfma_f32_32x32x16_bf16 v[16:31], v[224:227], v[244:247], v[16:31]
	v_exp_f32_e32 v78, v78
	v_exp_f32_e32 v79, v79
	v_add_f32_e32 v248, v248, v72
	v_add_f32_e32 v249, v249, v73
	v_add_f32_e32 v248, v248, v74
	v_add_f32_e32 v249, v249, v75
	v_add_f32_e32 v248, v248, v76
	v_add_f32_e32 v249, v249, v77
	v_add_f32_e32 v248, v248, v78
	v_add_f32_e32 v249, v249, v79
	v_cvt_pk_bf16_f32 v2, v72, v73
	v_cvt_pk_bf16_f32 v3, v74, v75
	v_cvt_pk_bf16_f32 v4, v76, v77
	v_cvt_pk_bf16_f32 v5, v78, v79
	s_nop 0
	s_waitcnt lgkmcnt(1)
	v_mfma_f32_32x32x16_bf16 v[32:47], v[228:231], v[2:5], v[32:47]
	s_waitcnt lgkmcnt(0)
	v_mfma_f32_32x32x16_bf16 v[16:31], v[232:235], v[2:5], v[16:31]
	s_add_i32 s8, s69, 3
	s_and_b32 s30, s8, 3
	s_mulk_i32 s30, 0x6000
	v_add_u32_e32 v0, s68, v136
	s_and_saveexec_b64 s[8:9], s[4:5]
	s_cbranch_execz .Lmy_m55b
	v_add_u32_e32 v2, 0xc0, v0
	v_mad_i64_i32 v[2:3], s[70:71], v2, s33, v[126:127]
	s_add_i32 m0, s30, s65
	s_nop 0
	global_load_lds_dwordx4 v[2:3], off

; #define STAGE8(Q, BASE, br, kt) do { const bf16_t* sb_ = (BASE) + ((long)(br) * K + (long)(kt) * BK8); \
;     _Pragma("unroll") for (int i_ = 0; i_ < 2; ++i_) \
;       __builtin_amdgcn_global_load_lds((const unsigned*)(sb_ + goff[i_]), (unsigned*)(smem + (Q) * HTB + i_ * 8192 + wu8 * 1024), 16, 0, 0); } while (0)
; #define WAIT_V8(n) asm volatile("s_waitcnt vmcnt(" #n ")" ::: "memory")
; #define BAR8 __builtin_amdgcn_s_barrier()
; DI void gemm8p(const bf16_t* __restrict__ A, const bf16_t* __restrict__ Bt, int K, f32x4v (&acc)[2][2][4][2], char* smem) {
;     ...
; #pragma unroll
;   for (int a = 0; a < 2; ++a)
; #pragma unroll
;     for (int b = 0; b < 2; ++b)
; #pragma unroll
;       for (int m = 0; m < 4; ++m)
; #pragma unroll
;         for (int n = 0; n < 2; ++n) acc[a][b][m][n] = f32x4v{0.f, 0.f, 0.f, 0.f};
;   bf16x8 At[4][2], B0[2][2], B1[2][2];
;   const int nt = K / BK8;
;   asm volatile("s_waitcnt vmcnt(0)" ::: "memory");
;   __syncthreads();
;   STAGE8(SB8(0, 0), Bt, 0, 0); STAGE8(SA8(0, 0), A, 0, 0);
;   STAGE8(SB8(0, 1), Bt, HALF8, 0); STAGE8(SA8(0, 1), A, HALF8, 0);
;   if (wr == 1) BAR8;
;   WAIT_V8(4); BAR8;
;   STAGE8(SB8(1, 0), Bt, 0, 1); STAGE8(SA8(1, 0), A, 0, 1); STAGE8(SB8(1, 1), Bt, HALF8, 1);
;   WAIT_V8(6); BAR8;
.LBB0_463:
	s_or_b64 exec, exec, s[8:9]
	s_xor_b64 s[6:7], s[6:7], -1
	v_writelane_b32 v250, s6, 12
	v_lshl_add_u64 v[2:3], v[2:3], 0, s[92:93]
	s_waitcnt vmcnt(4)
	s_barrier
	v_writelane_b32 v250, s7, 13
	s_add_i32 s6, s10, 0x18000
	s_mov_b32 m0, s6
	s_add_i32 s7, s10, 0x1a000
	global_load_lds_dwordx4 v[2:3], off
	v_lshl_add_u64 v[2:3], v[4:5], 0, s[92:93]
	s_mov_b32 m0, s7
	s_add_i32 s8, s10, 0x8000
	global_load_lds_dwordx4 v[2:3], off
	v_lshl_add_u64 v[2:3], v[8:9], 0, s[92:93]
	s_mov_b32 m0, s8
	s_add_i32 s9, s10, 0xa000
	global_load_lds_dwordx4 v[2:3], off
	v_lshl_add_u64 v[2:3], v[6:7], 0, s[92:93]
	s_mov_b32 m0, s9
	s_add_i32 s30, s10, 0x1c000
	global_load_lds_dwordx4 v[2:3], off
	v_lshl_add_u64 v[2:3], v[10:11], 0, s[92:93]
	s_mov_b32 m0, s30
	s_add_i32 s31, s10, 0x1e000
	global_load_lds_dwordx4 v[2:3], off
	v_lshl_add_u64 v[2:3], v[12:13], 0, s[92:93]
	s_mov_b32 m0, s31
	s_xor_b64 s[4:5], s[4:5], -1
	global_load_lds_dwordx4 v[2:3], off
	v_and_b32_e32 v23, 15, v148
	v_lshlrev_b32_e32 v24, 2, v148
	v_lshlrev_b32_e32 v21, 12, v21
	s_waitcnt vmcnt(6)
	v_add3_u32 v2, v20, v18, v19
	v_mov_b32_e32 v3, v1
	v_add3_u32 v4, v16, v14, v15
	v_mov_b32_e32 v5, v1
	v_writelane_b32 v250, s4, 14
	v_and_b32_e32 v22, 48, v148
	v_lshlrev_b32_e32 v23, 6, v23
	v_and_b32_e32 v24, 32, v24
	v_and_b32_e32 v21, 0x3000, v21
	v_lshlrev_b64 v[2:3], 1, v[2:3]
	v_lshlrev_b64 v[4:5], 1, v[4:5]
	s_lshl_b64 s[52:53], s[80:81], 8
	v_writelane_b32 v250, s5, 15
	v_lshlrev_b32_e32 v17, 13, v17
	v_or_b32_e32 v21, 0x10000, v21
	v_bitop3_b32 v22, v23, v24, v22 bitop3:0x36
	s_lshr_b32 s5, s80, 6
	v_lshl_add_u64 v[132:133], s[0:1], 0, v[2:3]
	v_lshl_add_u64 v[6:7], s[52:53], 0, v[2:3]
	v_lshl_add_u64 v[8:9], s[52:53], 0, v[4:5]
	v_lshl_add_u64 v[140:141], s[2:3], 0, v[2:3]
	v_mov_b32_e32 v2, 0
	s_lshl_b32 s4, s80, 7
	s_barrier
	s_add_i32 s35, s5, -2
	v_lshl_add_u64 v[134:135], s[0:1], 0, v[4:5]
	v_lshl_add_u64 v[136:137], s[2:3], 0, v[6:7]
	v_lshl_add_u64 v[138:139], s[2:3], 0, v[8:9]
	v_lshl_add_u64 v[142:143], s[2:3], 0, v[4:5]
	v_lshl_add_u64 v[144:145], s[0:1], 0, v[8:9]
	v_lshl_add_u64 v[146:147], s[0:1], 0, v[6:7]
	s_mov_b32 s52, 0
	s_mov_b64 s[2:3], 0
	s_add_i32 s34, s10, 0xe000
	v_add_u32_e32 v150, v21, v22
	v_add_u32_e32 v149, v17, v22
	v_mov_b32_e32 v3, v2
	v_mov_b32_e32 v4, v2
	v_mov_b32_e32 v5, v2
	v_mov_b32_e32 v6, v2
	v_mov_b32_e32 v7, v2
	v_mov_b32_e32 v8, v2
	v_mov_b32_e32 v9, v2
	v_mov_b32_e32 v10, v2
	v_mov_b32_e32 v11, v2
	v_mov_b32_e32 v12, v2
	v_mov_b32_e32 v13, v2
	v_mov_b32_e32 v14, v2
	v_mov_b32_e32 v15, v2
	v_mov_b32_e32 v16, v2
	v_mov_b32_e32 v17, v2
	v_mov_b32_e32 v18, v2
	v_mov_b32_e32 v19, v2
	v_mov_b32_e32 v20, v2
	v_mov_b32_e32 v21, v2
	v_mov_b32_e32 v22, v2
	v_mov_b32_e32 v23, v2
	v_mov_b32_e32 v24, v2
	v_mov_b32_e32 v25, v2
	v_mov_b32_e32 v26, v2
	v_mov_b32_e32 v27, v2
	v_mov_b32_e32 v28, v2
	v_mov_b32_e32 v29, v2
	v_mov_b32_e32 v30, v2
	v_mov_b32_e32 v31, v2
	v_mov_b32_e32 v32, v2
	v_mov_b32_e32 v33, v2
	v_mov_b32_e32 v34, v2
	v_mov_b32_e32 v35, v2
	v_mov_b32_e32 v36, v2
	v_mov_b32_e32 v37, v2
	v_mov_b32_e32 v38, v2
	v_mov_b32_e32 v39, v2
	v_mov_b32_e32 v40, v2
	v_mov_b32_e32 v41, v2
	v_mov_b32_e32 v42, v2
	v_mov_b32_e32 v43, v2
	v_mov_b32_e32 v44, v2
	v_mov_b32_e32 v45, v2
	v_mov_b32_e32 v46, v2
	v_mov_b32_e32 v47, v2
	v_mov_b32_e32 v48, v2
	v_mov_b32_e32 v49, v2
	v_mov_b32_e32 v50, v2
	v_mov_b32_e32 v51, v2
	v_mov_b32_e32 v52, v2
	v_mov_b32_e32 v53, v2
	v_mov_b32_e32 v54, v2
	v_mov_b32_e32 v55, v2
	v_mov_b32_e32 v56, v2
	v_mov_b32_e32 v57, v2
	v_mov_b32_e32 v58, v2
	v_mov_b32_e32 v59, v2
	v_mov_b32_e32 v60, v2
	v_mov_b32_e32 v61, v2
	v_mov_b32_e32 v62, v2
	v_mov_b32_e32 v63, v2
	v_mov_b32_e32 v64, v2
	v_mov_b32_e32 v65, v2
	v_mov_b32_e32 v66, v2
	v_mov_b32_e32 v67, v2
	v_mov_b32_e32 v68, v2
	v_mov_b32_e32 v69, v2
	v_mov_b32_e32 v70, v2
	v_mov_b32_e32 v71, v2
	v_mov_b32_e32 v72, v2
	v_mov_b32_e32 v73, v2
	v_mov_b32_e32 v74, v2
	v_mov_b32_e32 v75, v2
	v_mov_b32_e32 v76, v2
	v_mov_b32_e32 v77, v2
	v_mov_b32_e32 v78, v2
	v_mov_b32_e32 v79, v2
	v_mov_b32_e32 v80, v2
	v_mov_b32_e32 v81, v2
	v_mov_b32_e32 v82, v2
	v_mov_b32_e32 v83, v2
	v_mov_b32_e32 v84, v2
	v_mov_b32_e32 v85, v2
	v_mov_b32_e32 v86, v2
	v_mov_b32_e32 v87, v2
	v_mov_b32_e32 v88, v2
	v_mov_b32_e32 v89, v2
	v_mov_b32_e32 v90, v2
	v_mov_b32_e32 v91, v2
	v_mov_b32_e32 v92, v2
	v_mov_b32_e32 v93, v2
	v_mov_b32_e32 v94, v2
	v_mov_b32_e32 v95, v2
	v_mov_b32_e32 v96, v2
	v_mov_b32_e32 v97, v2
	v_mov_b32_e32 v98, v2
	v_mov_b32_e32 v99, v2
	v_mov_b32_e32 v100, v2
	v_mov_b32_e32 v101, v2
	v_mov_b32_e32 v102, v2
	v_mov_b32_e32 v103, v2
	v_mov_b32_e32 v104, v2
	v_mov_b32_e32 v105, v2
	v_mov_b32_e32 v106, v2
	v_mov_b32_e32 v107, v2
	v_mov_b32_e32 v108, v2
	v_mov_b32_e32 v109, v2
	v_mov_b32_e32 v110, v2
	v_mov_b32_e32 v111, v2
	v_mov_b32_e32 v112, v2
	v_mov_b32_e32 v113, v2
	v_mov_b32_e32 v114, v2
	v_mov_b32_e32 v115, v2
	v_mov_b32_e32 v116, v2
	v_mov_b32_e32 v117, v2
	v_mov_b32_e32 v118, v2
	v_mov_b32_e32 v119, v2
	v_mov_b32_e32 v120, v2
	v_mov_b32_e32 v121, v2
	v_mov_b32_e32 v122, v2
	v_mov_b32_e32 v123, v2
	v_mov_b32_e32 v124, v2
	v_mov_b32_e32 v125, v2
	v_mov_b32_e32 v126, v2
	v_mov_b32_e32 v127, v2
	v_mov_b32_e32 v128, v2
	v_mov_b32_e32 v129, v2
	s_nop 0
	s_nop 0
	s_nop 0
	s_nop 0
	s_nop 0
	s_nop 0
	s_nop 0
	s_nop 0
	s_nop 0
	s_nop 0
	s_nop 0
	s_nop 0
	s_nop 0
	s_nop 0
	s_nop 0
	s_nop 0
	s_nop 0
	s_nop 0
